# offload ranges shifted: prologue converts only layer-0 W_in/W_out; FFN + mixer weights of layer l and W_in/W_out of layer l+1 are converted by the idle workgroups during layer l's in-proj GEMM
# baseline (speedup 1.0000x reference)
; #define LAS __attribute__((address_space(3)))
; __device__ __forceinline__ void phase_prologue(KP p, LAS unsigned char* lds) {
;     ...
;     for (int it = gw; it < DEPTH * I_LAYER; it += NGW) {
; __global__ void __launch_bounds__(512) fwd_kernel(Params p_arg) {
;     ...
;         if (sub == 0) {
;             pg8::Gemm g{(const bf16_t*)(ws + OFF_HB), (const bf16_t*)(ws + OFF_WIN + l * SZ_WIN), M_TOK, DIN_P, DM};
;             S.init(M_TOK, DIN_P, gridDim.x, blockIdx.x);
;             LAS float* rstab = (LAS float*)(lds + pg8::STAGE_BYTES);
;             pg8::build_rs_table(rstab, S, (const float*)(ws + OFF_SSQA));
;             pg8::EpiScaleBf16<0> E{(bf16_t*)(ws + OFF_ZB), DIN_P, rstab};
;             pg8::gemm_phase(lds, g, S, E);
.LBB0_468:
	v_readlane_b32 s22, v254, 46
	v_readlane_b32 s23, v254, 47
	s_cmp_lt_u32 s2, 0x80
	s_cbranch_scc1 .LA_nooff
	s_movk_i32 s6, 0x530
	s_cmp_eq_u32 s82, 1
	s_cbranch_scc1 .LA_off
	s_movk_i32 s6, 0x1acc
	s_cmp_eq_u32 s82, 8
	s_cbranch_scc1 .LA_off
	s_movk_i32 s6, 0x3068
	s_cmp_eq_u32 s82, 15
	s_cbranch_scc1 .LA_off
	s_movk_i32 s6, 0x4604
	s_cmp_eq_u32 s82, 22
	s_cbranch_scc0 .LA_nooff

; __device__ __forceinline__ void phase_prologue(KP p, LAS unsigned char* lds) {
;     ...
;     for (int it = gw; it < DEPTH * I_LAYER; it += NGW) {
;         const int l = it / I_LAYER; int r = it % I_LAYER;
;         if (r < I_IN) { transpose_item(p->w_in + (size_t)l * DM * DIN, DIN, p->mix_norm_g + l * DM, nullptr, (bf16_t*)(ws + OFF_WIN + l * SZ_WIN), DM, scr, r, lane); continue; } r -= I_IN;
.LBB0_469:
	s_waitcnt vmcnt(0)
	v_mov_b32_e32 v22, v167
	v_readlane_b32 s4, v253, 54
	v_readlane_b32 s6, v252, 62
	s_movk_i32 s101, 0x530
	s_mov_b32 s100, s33
	s_nop 1
	s_cmp_eq_u32 s6, 0
	s_cbranch_scc1 .Lpro_go
	s_sub_i32 s4, s2, 0x80
	s_lshl_b32 s4, s4, 3
	s_add_i32 s4, s4, s6
	s_add_i32 s101, s6, 0x159c
	s_min_u32 s101, s101, 0x5670
	s_movk_i32 s100, 0x400
